# speedup vs baseline: 1.0267x; 1.0056x over previous
;     __device__ __forceinline__ void operator()(const f32x4 (&acc)[2][2][4][2], const Unit& u, int wr, int wc, int fr, int fq) const {
;         const int col0 = u.pn * BM + wc * 32 + 4 * fq;
; #pragma unroll
;         for (int ai = 0; ai < 2; ++ai)
; #pragma unroll
;             for (int m = 0; m < 4; ++m) { const size_t row = (size_t)(u.pm * BM + ai * HALF + wr * 64 + m * 16 + fr);
; #pragma unroll
;                 for (int bj = 0; bj < 2; ++bj)
; #pragma unroll
;                     for (int n = 0; n < 2; ++n) { const int col = col0 + bj * HALF + n * 16; const f32x4 bv = *(const f32x4*)(bias + col), vv = *(const f32x4*)(V + row * ldv + col);
;                         const f32x4 z = acc[ai][bj][m][n] + bv; f32x4 o;
; #pragma unroll
;                         for (int j = 0; j < 4; ++j) o[j] = vv[j] * __builtin_amdgcn_rcpf(1.f + __expf(-z[j]));
;                         *(f32x4*)(Y + row * ldy + col) = o; } }
.LBB0_136:
	v_lshl_or_b32 v136, s1, 8, v149
	v_ashrrev_i32_e32 v137, 31, v136
	v_lshlrev_b64 v[138:139], 2, v[136:137]
	v_lshl_add_u64 v[136:137], s[10:11], 0, v[138:139]
	global_load_dwordx4 v[152:155], v[136:137], off
	v_lshl_add_u32 v140, s0, 8, v145
	v_ashrrev_i32_e32 v141, 31, v140
	v_lshlrev_b64 v[142:143], 11, v[140:141]
	v_lshl_add_u64 v[142:143], s[8:9], 0, v[142:143]
	v_lshl_add_u64 v[142:143], v[142:143], 0, v[138:139]
	global_load_dwordx4 v[156:159], v[142:143], off
	v_lshlrev_b64 v[160:161], 13, v[140:141]
	s_andn2_b64 vcc, exec, s[22:23]
	s_mov_b64 s[0:1], -1
	s_movk_i32 s26, 0x1000
	global_load_dwordx4 v[190:193], v[136:137], off
	global_load_dwordx4 v[194:197], v[136:137], off offset:64
	global_load_dwordx4 v[198:201], v[136:137], off offset:512
	global_load_dwordx4 v[202:205], v[136:137], off offset:576
	v_add_u32_e32 v238, 0x0, v140
	v_mov_b32_e32 v239, 0
	v_lshlrev_b64 v[238:239], 11, v[238:239]
	v_lshl_add_u64 v[238:239], s[8:9], 0, v[238:239]
	v_lshl_add_u64 v[238:239], v[238:239], 0, v[138:139]
	global_load_dwordx4 v[206:209], v[238:239], off
	global_load_dwordx4 v[210:213], v[238:239], off offset:64
	global_load_dwordx4 v[214:217], v[238:239], off offset:512
	global_load_dwordx4 v[218:221], v[238:239], off offset:576
	v_add_u32_e32 v240, 0x10, v140
	v_mov_b32_e32 v241, 0
	v_lshlrev_b64 v[240:241], 11, v[240:241]
	v_lshl_add_u64 v[240:241], s[8:9], 0, v[240:241]
	v_lshl_add_u64 v[240:241], v[240:241], 0, v[138:139]
	global_load_dwordx4 v[222:225], v[240:241], off
	global_load_dwordx4 v[226:229], v[240:241], off offset:64
	global_load_dwordx4 v[230:233], v[240:241], off offset:512
	global_load_dwordx4 v[234:237], v[240:241], off offset:576
	s_waitcnt vmcnt(0)
	v_add_f32_e32 v124, v124, v152
	v_add_f32_e32 v125, v125, v153
	v_add_f32_e32 v126, v126, v154
	v_add_f32_e32 v127, v127, v155
	v_mul_f32_e32 v124, 0xbfb8aa3b, v124
	v_mul_f32_e32 v125, 0xbfb8aa3b, v125
	v_mul_f32_e32 v126, 0xbfb8aa3b, v126
	v_mul_f32_e32 v127, 0xbfb8aa3b, v127
	v_exp_f32_e32 v124, v124
	v_exp_f32_e32 v125, v125
	v_exp_f32_e32 v126, v126
	v_exp_f32_e32 v127, v127
	v_add_f32_e32 v124, 1.0, v124
	v_add_f32_e32 v125, 1.0, v125
	v_add_f32_e32 v141, 1.0, v126
	v_add_f32_e32 v127, 1.0, v127
	v_rcp_f32_e32 v126, v124
	v_rcp_f32_e32 v152, v141
	v_rcp_f32_e32 v153, v127
	v_rcp_f32_e32 v127, v125
	v_lshl_add_u64 v[124:125], s[4:5], 0, v[160:161]
	v_lshl_add_u64 v[124:125], v[124:125], 0, v[138:139]
	v_pk_mul_f32 v[154:155], v[158:159], v[152:153]
	v_pk_mul_f32 v[152:153], v[156:157], v[126:127]
	global_store_dwordx4 v[124:125], v[152:155], off
	s_nop 1
	v_mov_b64_e32 v[152:153], v[194:195]
	v_mov_b64_e32 v[154:155], v[196:197]
	s_nop 0
	s_nop 1
	v_mov_b64_e32 v[156:157], v[210:211]
	v_mov_b64_e32 v[158:159], v[212:213]
	v_add_f32_e32 v120, v120, v152
	v_add_f32_e32 v121, v121, v153
	v_add_f32_e32 v122, v122, v154
	v_add_f32_e32 v123, v123, v155
	v_mul_f32_e32 v120, 0xbfb8aa3b, v120
	v_mul_f32_e32 v121, 0xbfb8aa3b, v121
	v_mul_f32_e32 v122, 0xbfb8aa3b, v122
	v_mul_f32_e32 v123, 0xbfb8aa3b, v123
	v_exp_f32_e32 v120, v120
	v_exp_f32_e32 v121, v121
	v_exp_f32_e32 v122, v122
	v_exp_f32_e32 v123, v123
	v_add_f32_e32 v120, 1.0, v120
	v_add_f32_e32 v121, 1.0, v121
	v_add_f32_e32 v122, 1.0, v122
	v_add_f32_e32 v123, 1.0, v123
	v_rcp_f32_e32 v120, v120
	v_rcp_f32_e32 v122, v122
	v_rcp_f32_e32 v123, v123
	v_rcp_f32_e32 v121, v121
	v_pk_mul_f32 v[122:123], v[158:159], v[122:123]
	v_pk_mul_f32 v[120:121], v[156:157], v[120:121]
	global_store_dwordx4 v[124:125], v[120:123], off offset:64
	s_nop 1
	v_mov_b64_e32 v[120:121], v[198:199]
	v_mov_b64_e32 v[122:123], v[200:201]
	s_nop 0
	s_nop 1
	v_mov_b64_e32 v[152:153], v[214:215]
	v_mov_b64_e32 v[154:155], v[216:217]
	v_add_f32_e32 v116, v116, v120
	v_add_f32_e32 v117, v117, v121
	v_add_f32_e32 v118, v118, v122
	v_add_f32_e32 v119, v119, v123
	v_mul_f32_e32 v116, 0xbfb8aa3b, v116
	v_mul_f32_e32 v117, 0xbfb8aa3b, v117
	v_mul_f32_e32 v118, 0xbfb8aa3b, v118
	v_mul_f32_e32 v119, 0xbfb8aa3b, v119
	v_exp_f32_e32 v116, v116
	v_exp_f32_e32 v117, v117
	v_exp_f32_e32 v118, v118
	v_exp_f32_e32 v119, v119
	v_add_f32_e32 v116, 1.0, v116
	v_add_f32_e32 v117, 1.0, v117
	v_add_f32_e32 v118, 1.0, v118
	v_add_f32_e32 v119, 1.0, v119
	v_rcp_f32_e32 v116, v116
	v_rcp_f32_e32 v118, v118
	v_rcp_f32_e32 v119, v119
	v_rcp_f32_e32 v117, v117
	v_pk_mul_f32 v[118:119], v[154:155], v[118:119]
	v_pk_mul_f32 v[116:117], v[152:153], v[116:117]
	global_store_dwordx4 v[124:125], v[116:119], off offset:512
	s_nop 1
	v_mov_b64_e32 v[116:117], v[202:203]
	v_mov_b64_e32 v[118:119], v[204:205]
	s_nop 0
	s_nop 1
	v_mov_b64_e32 v[120:121], v[218:219]
	v_mov_b64_e32 v[122:123], v[220:221]
	v_add_f32_e32 v112, v112, v116
	v_add_f32_e32 v113, v113, v117
	v_add_f32_e32 v114, v114, v118
	v_add_f32_e32 v115, v115, v119
	v_mul_f32_e32 v112, 0xbfb8aa3b, v112
	v_mul_f32_e32 v113, 0xbfb8aa3b, v113
	v_mul_f32_e32 v114, 0xbfb8aa3b, v114
	v_mul_f32_e32 v115, 0xbfb8aa3b, v115
	v_exp_f32_e32 v112, v112
	v_exp_f32_e32 v113, v113
	v_exp_f32_e32 v114, v114
	v_exp_f32_e32 v115, v115
	v_add_f32_e32 v112, 1.0, v112
	v_add_f32_e32 v113, 1.0, v113
	v_add_f32_e32 v114, 1.0, v114
	v_add_f32_e32 v115, 1.0, v115
	v_rcp_f32_e32 v112, v112
	v_rcp_f32_e32 v114, v114
	v_rcp_f32_e32 v115, v115
	v_rcp_f32_e32 v113, v113
	v_pk_mul_f32 v[114:115], v[122:123], v[114:115]
	v_pk_mul_f32 v[112:113], v[120:121], v[112:113]
	global_store_dwordx4 v[124:125], v[112:115], off offset:576
	s_nop 1
	v_mov_b64_e32 v[114:115], v[190:191]
	v_mov_b64_e32 v[116:117], v[192:193]
	v_or_b32_e32 v122, 16, v140
	v_ashrrev_i32_e32 v123, 31, v122
	v_lshlrev_b64 v[112:113], 11, v[122:123]
	v_lshl_add_u64 v[112:113], s[8:9], 0, v[112:113]
;     __device__ __forceinline__ void operator()(const f32x4 (&acc)[2][2][4][2], const Unit& u, int wr, int wc, int fr, int fq) const {
;         const int col0 = u.pn * BM + wc * 32 + 4 * fq;
; #pragma unroll
;         for (int ai = 0; ai < 2; ++ai)
; #pragma unroll
;             for (int m = 0; m < 4; ++m) { const size_t row = (size_t)(u.pm * BM + ai * HALF + wr * 64 + m * 16 + fr);
; #pragma unroll
;                 for (int bj = 0; bj < 2; ++bj)
; #pragma unroll
;                     for (int n = 0; n < 2; ++n) { const int col = col0 + bj * HALF + n * 16; const f32x4 bv = *(const f32x4*)(bias + col), vv = *(const f32x4*)(V + row * ldv + col);
;                         const f32x4 z = acc[ai][bj][m][n] + bv; f32x4 o;
; #pragma unroll
;                         for (int j = 0; j < 4; ++j) o[j] = vv[j] * __builtin_amdgcn_rcpf(1.f + __expf(-z[j]));
;                         *(f32x4*)(Y + row * ldy + col) = o; } }
	v_lshl_add_u64 v[112:113], v[112:113], 0, v[138:139]
	s_nop 1
	v_mov_b64_e32 v[118:119], v[222:223]
	v_mov_b64_e32 v[120:121], v[224:225]
	v_lshlrev_b64 v[122:123], 13, v[122:123]
	v_add_f32_e32 v108, v108, v114
	v_add_f32_e32 v109, v109, v115
	v_add_f32_e32 v110, v110, v116
	v_add_f32_e32 v111, v111, v117
	v_mul_f32_e32 v108, 0xbfb8aa3b, v108
	v_mul_f32_e32 v109, 0xbfb8aa3b, v109
	v_mul_f32_e32 v110, 0xbfb8aa3b, v110
	v_mul_f32_e32 v111, 0xbfb8aa3b, v111
	v_exp_f32_e32 v108, v108
	v_exp_f32_e32 v109, v109
	v_exp_f32_e32 v110, v110
	v_exp_f32_e32 v111, v111
	v_add_f32_e32 v108, 1.0, v108
	v_add_f32_e32 v109, 1.0, v109
	v_add_f32_e32 v114, 1.0, v110
	v_add_f32_e32 v111, 1.0, v111
	v_rcp_f32_e32 v110, v108
	v_rcp_f32_e32 v114, v114
	v_rcp_f32_e32 v115, v111
	v_rcp_f32_e32 v111, v109
	v_lshl_add_u64 v[108:109], s[4:5], 0, v[122:123]
	v_lshl_add_u64 v[108:109], v[108:109], 0, v[138:139]
	v_pk_mul_f32 v[116:117], v[120:121], v[114:115]
	v_pk_mul_f32 v[114:115], v[118:119], v[110:111]
	global_store_dwordx4 v[108:109], v[114:117], off
	s_nop 1
	v_mov_b64_e32 v[114:115], v[194:195]
	v_mov_b64_e32 v[116:117], v[196:197]
	s_nop 0
	s_nop 1
	v_mov_b64_e32 v[118:119], v[226:227]
	v_mov_b64_e32 v[120:121], v[228:229]
	v_add_f32_e32 v104, v104, v114
	v_add_f32_e32 v105, v105, v115
	v_add_f32_e32 v106, v106, v116
	v_add_f32_e32 v107, v107, v117
	v_mul_f32_e32 v104, 0xbfb8aa3b, v104
	v_mul_f32_e32 v105, 0xbfb8aa3b, v105
	v_mul_f32_e32 v106, 0xbfb8aa3b, v106
	v_mul_f32_e32 v107, 0xbfb8aa3b, v107
	v_exp_f32_e32 v104, v104
	v_exp_f32_e32 v105, v105
	v_exp_f32_e32 v106, v106
	v_exp_f32_e32 v107, v107
	v_add_f32_e32 v104, 1.0, v104
	v_add_f32_e32 v105, 1.0, v105
	v_add_f32_e32 v106, 1.0, v106
	v_add_f32_e32 v107, 1.0, v107
	v_rcp_f32_e32 v104, v104
	v_rcp_f32_e32 v106, v106
	v_rcp_f32_e32 v107, v107
	v_rcp_f32_e32 v105, v105
	v_pk_mul_f32 v[106:107], v[120:121], v[106:107]
	v_pk_mul_f32 v[104:105], v[118:119], v[104:105]
	global_store_dwordx4 v[108:109], v[104:107], off offset:64
	s_nop 1
	v_mov_b64_e32 v[104:105], v[198:199]
	v_mov_b64_e32 v[106:107], v[200:201]
	s_nop 0
	s_nop 1
	v_mov_b64_e32 v[114:115], v[230:231]
	v_mov_b64_e32 v[116:117], v[232:233]
	v_add_f32_e32 v100, v100, v104
	v_add_f32_e32 v101, v101, v105
	v_add_f32_e32 v102, v102, v106
	v_add_f32_e32 v103, v103, v107
	v_mul_f32_e32 v100, 0xbfb8aa3b, v100
	v_mul_f32_e32 v101, 0xbfb8aa3b, v101
	v_mul_f32_e32 v102, 0xbfb8aa3b, v102
	v_mul_f32_e32 v103, 0xbfb8aa3b, v103
	v_exp_f32_e32 v100, v100
	v_exp_f32_e32 v101, v101
	v_exp_f32_e32 v102, v102
	v_exp_f32_e32 v103, v103
	v_add_f32_e32 v100, 1.0, v100
	v_add_f32_e32 v101, 1.0, v101
	v_add_f32_e32 v102, 1.0, v102
	v_add_f32_e32 v103, 1.0, v103
	v_rcp_f32_e32 v100, v100
	v_rcp_f32_e32 v102, v102
	v_rcp_f32_e32 v103, v103
	v_rcp_f32_e32 v101, v101
	v_pk_mul_f32 v[102:103], v[116:117], v[102:103]
	v_pk_mul_f32 v[100:101], v[114:115], v[100:101]
	global_store_dwordx4 v[108:109], v[100:103], off offset:512
	s_nop 1
	v_mov_b64_e32 v[100:101], v[202:203]
	v_mov_b64_e32 v[102:103], v[204:205]
	s_nop 0
	s_nop 1
	v_mov_b64_e32 v[104:105], v[234:235]
	v_mov_b64_e32 v[106:107], v[236:237]
	v_add_f32_e32 v96, v96, v100
	v_add_f32_e32 v97, v97, v101
	v_add_f32_e32 v98, v98, v102
	v_add_f32_e32 v99, v99, v103
	v_mul_f32_e32 v96, 0xbfb8aa3b, v96
	v_mul_f32_e32 v97, 0xbfb8aa3b, v97
	v_mul_f32_e32 v98, 0xbfb8aa3b, v98
	v_mul_f32_e32 v99, 0xbfb8aa3b, v99
	v_exp_f32_e32 v96, v96
	v_exp_f32_e32 v97, v97
	v_exp_f32_e32 v98, v98
	v_exp_f32_e32 v99, v99
	v_add_f32_e32 v96, 1.0, v96
	v_add_f32_e32 v97, 1.0, v97
	v_add_f32_e32 v98, 1.0, v98
	v_add_f32_e32 v99, 1.0, v99
	v_rcp_f32_e32 v96, v96
	v_rcp_f32_e32 v98, v98
	v_rcp_f32_e32 v99, v99
	v_rcp_f32_e32 v97, v97
	v_pk_mul_f32 v[98:99], v[106:107], v[98:99]
	v_pk_mul_f32 v[96:97], v[104:105], v[96:97]
	global_store_dwordx4 v[108:109], v[96:99], off offset:576
	s_nop 1
	v_mov_b64_e32 v[98:99], v[190:191]
	v_mov_b64_e32 v[100:101], v[192:193]
	v_add_u32_e32 v238, 0x20, v140
	v_mov_b32_e32 v239, 0
	v_lshlrev_b64 v[238:239], 11, v[238:239]
	v_lshl_add_u64 v[238:239], s[8:9], 0, v[238:239]
	v_lshl_add_u64 v[238:239], v[238:239], 0, v[138:139]
	global_load_dwordx4 v[206:209], v[238:239], off
	global_load_dwordx4 v[210:213], v[238:239], off offset:64
	global_load_dwordx4 v[214:217], v[238:239], off offset:512
	global_load_dwordx4 v[218:221], v[238:239], off offset:576
	v_add_u32_e32 v240, 0x30, v140
	v_mov_b32_e32 v241, 0
	v_lshlrev_b64 v[240:241], 11, v[240:241]
	v_lshl_add_u64 v[240:241], s[8:9], 0, v[240:241]
	v_lshl_add_u64 v[240:241], v[240:241], 0, v[138:139]
	global_load_dwordx4 v[222:225], v[240:241], off
	global_load_dwordx4 v[226:229], v[240:241], off offset:64
	global_load_dwordx4 v[230:233], v[240:241], off offset:512
	global_load_dwordx4 v[234:237], v[240:241], off offset:576
	s_waitcnt vmcnt(0)
;     __device__ __forceinline__ void operator()(const f32x4 (&acc)[2][2][4][2], const Unit& u, int wr, int wc, int fr, int fq) const {
;         const int col0 = u.pn * BM + wc * 32 + 4 * fq;
; #pragma unroll
;         for (int ai = 0; ai < 2; ++ai)
; #pragma unroll
;             for (int m = 0; m < 4; ++m) { const size_t row = (size_t)(u.pm * BM + ai * HALF + wr * 64 + m * 16 + fr);
; #pragma unroll
;                 for (int bj = 0; bj < 2; ++bj)
; #pragma unroll
;                     for (int n = 0; n < 2; ++n) { const int col = col0 + bj * HALF + n * 16; const f32x4 bv = *(const f32x4*)(bias + col), vv = *(const f32x4*)(V + row * ldv + col);
;                         const f32x4 z = acc[ai][bj][m][n] + bv; f32x4 o;
; #pragma unroll
;                         for (int j = 0; j < 4; ++j) o[j] = vv[j] * __builtin_amdgcn_rcpf(1.f + __expf(-z[j]));
;                         *(f32x4*)(Y + row * ldy + col) = o; } }
	v_or_b32_e32 v106, 32, v140
	v_ashrrev_i32_e32 v107, 31, v106
	v_lshlrev_b64 v[96:97], 11, v[106:107]
	v_lshl_add_u64 v[96:97], s[8:9], 0, v[96:97]
	v_lshl_add_u64 v[96:97], v[96:97], 0, v[138:139]
	s_nop 1
	v_mov_b64_e32 v[102:103], v[206:207]
	v_mov_b64_e32 v[104:105], v[208:209]
	v_lshlrev_b64 v[106:107], 13, v[106:107]
	v_add_f32_e32 v92, v92, v98
	v_add_f32_e32 v93, v93, v99
	v_add_f32_e32 v94, v94, v100
	v_add_f32_e32 v95, v95, v101
	v_mul_f32_e32 v92, 0xbfb8aa3b, v92
	v_mul_f32_e32 v93, 0xbfb8aa3b, v93
	v_mul_f32_e32 v94, 0xbfb8aa3b, v94
	v_mul_f32_e32 v95, 0xbfb8aa3b, v95
	v_exp_f32_e32 v92, v92
	v_exp_f32_e32 v93, v93
	v_exp_f32_e32 v94, v94
	v_exp_f32_e32 v95, v95
	v_add_f32_e32 v92, 1.0, v92
	v_add_f32_e32 v93, 1.0, v93
	v_add_f32_e32 v98, 1.0, v94
	v_add_f32_e32 v95, 1.0, v95
	v_rcp_f32_e32 v94, v92
	v_rcp_f32_e32 v98, v98
	v_rcp_f32_e32 v99, v95
	v_rcp_f32_e32 v95, v93
	v_lshl_add_u64 v[92:93], s[4:5], 0, v[106:107]
	v_lshl_add_u64 v[92:93], v[92:93], 0, v[138:139]
	v_pk_mul_f32 v[100:101], v[104:105], v[98:99]
	v_pk_mul_f32 v[98:99], v[102:103], v[94:95]
	global_store_dwordx4 v[92:93], v[98:101], off
	s_nop 1
	v_mov_b64_e32 v[98:99], v[194:195]
	v_mov_b64_e32 v[100:101], v[196:197]
	s_nop 0
	s_nop 1
	v_mov_b64_e32 v[102:103], v[210:211]
	v_mov_b64_e32 v[104:105], v[212:213]
	v_add_f32_e32 v88, v88, v98
	v_add_f32_e32 v89, v89, v99
	v_add_f32_e32 v90, v90, v100
	v_add_f32_e32 v91, v91, v101
	v_mul_f32_e32 v88, 0xbfb8aa3b, v88
	v_mul_f32_e32 v89, 0xbfb8aa3b, v89
	v_mul_f32_e32 v90, 0xbfb8aa3b, v90
	v_mul_f32_e32 v91, 0xbfb8aa3b, v91
	v_exp_f32_e32 v88, v88
	v_exp_f32_e32 v89, v89
	v_exp_f32_e32 v90, v90
	v_exp_f32_e32 v91, v91
	v_add_f32_e32 v88, 1.0, v88
	v_add_f32_e32 v89, 1.0, v89
	v_add_f32_e32 v90, 1.0, v90
	v_add_f32_e32 v91, 1.0, v91
	v_rcp_f32_e32 v88, v88
	v_rcp_f32_e32 v90, v90
	v_rcp_f32_e32 v91, v91
	v_rcp_f32_e32 v89, v89
	v_pk_mul_f32 v[90:91], v[104:105], v[90:91]
	v_pk_mul_f32 v[88:89], v[102:103], v[88:89]
	global_store_dwordx4 v[92:93], v[88:91], off offset:64
	s_nop 1
	v_mov_b64_e32 v[88:89], v[198:199]
	v_mov_b64_e32 v[90:91], v[200:201]
	s_nop 0
	s_nop 1
	v_mov_b64_e32 v[98:99], v[214:215]
	v_mov_b64_e32 v[100:101], v[216:217]
	v_add_f32_e32 v84, v84, v88
	v_add_f32_e32 v85, v85, v89
	v_add_f32_e32 v86, v86, v90
	v_add_f32_e32 v87, v87, v91
	v_mul_f32_e32 v84, 0xbfb8aa3b, v84
	v_mul_f32_e32 v85, 0xbfb8aa3b, v85
	v_mul_f32_e32 v86, 0xbfb8aa3b, v86
	v_mul_f32_e32 v87, 0xbfb8aa3b, v87
	v_exp_f32_e32 v84, v84
	v_exp_f32_e32 v85, v85
	v_exp_f32_e32 v86, v86
	v_exp_f32_e32 v87, v87
	v_add_f32_e32 v84, 1.0, v84
	v_add_f32_e32 v85, 1.0, v85
	v_add_f32_e32 v86, 1.0, v86
	v_add_f32_e32 v87, 1.0, v87
	v_rcp_f32_e32 v84, v84
	v_rcp_f32_e32 v86, v86
	v_rcp_f32_e32 v87, v87
	v_rcp_f32_e32 v85, v85
	v_pk_mul_f32 v[86:87], v[100:101], v[86:87]
	v_pk_mul_f32 v[84:85], v[98:99], v[84:85]
	global_store_dwordx4 v[92:93], v[84:87], off offset:512
	s_nop 1
	v_mov_b64_e32 v[84:85], v[202:203]
	v_mov_b64_e32 v[86:87], v[204:205]
	s_nop 0
	s_nop 1
	v_mov_b64_e32 v[88:89], v[218:219]
	v_mov_b64_e32 v[90:91], v[220:221]
	v_add_f32_e32 v80, v80, v84
	v_add_f32_e32 v81, v81, v85
	v_add_f32_e32 v82, v82, v86
	v_add_f32_e32 v83, v83, v87
	v_mul_f32_e32 v80, 0xbfb8aa3b, v80
	v_mul_f32_e32 v81, 0xbfb8aa3b, v81
	v_mul_f32_e32 v82, 0xbfb8aa3b, v82
	v_mul_f32_e32 v83, 0xbfb8aa3b, v83
	v_exp_f32_e32 v80, v80
	v_exp_f32_e32 v81, v81
	v_exp_f32_e32 v82, v82
	v_exp_f32_e32 v83, v83
	v_add_f32_e32 v80, 1.0, v80
	v_add_f32_e32 v81, 1.0, v81
	v_add_f32_e32 v82, 1.0, v82
	v_add_f32_e32 v83, 1.0, v83
	v_rcp_f32_e32 v80, v80
	v_rcp_f32_e32 v82, v82
	v_rcp_f32_e32 v83, v83
	v_rcp_f32_e32 v81, v81
	v_pk_mul_f32 v[82:83], v[90:91], v[82:83]
	v_pk_mul_f32 v[80:81], v[88:89], v[80:81]
	global_store_dwordx4 v[92:93], v[80:83], off offset:576
	s_nop 1
	v_mov_b64_e32 v[82:83], v[190:191]
	v_mov_b64_e32 v[84:85], v[192:193]
	v_or_b32_e32 v90, 48, v140
	v_ashrrev_i32_e32 v91, 31, v90
	v_lshlrev_b64 v[80:81], 11, v[90:91]
	v_lshl_add_u64 v[80:81], s[8:9], 0, v[80:81]
	v_lshl_add_u64 v[80:81], v[80:81], 0, v[138:139]
	s_nop 1
	v_mov_b64_e32 v[86:87], v[222:223]
	v_mov_b64_e32 v[88:89], v[224:225]
	v_lshlrev_b64 v[90:91], 13, v[90:91]
	v_add_f32_e32 v76, v76, v82
	v_add_f32_e32 v77, v77, v83
	v_add_f32_e32 v78, v78, v84
	v_add_f32_e32 v79, v79, v85
	v_mul_f32_e32 v76, 0xbfb8aa3b, v76
	v_mul_f32_e32 v77, 0xbfb8aa3b, v77
	v_mul_f32_e32 v78, 0xbfb8aa3b, v78
	v_mul_f32_e32 v79, 0xbfb8aa3b, v79
	v_exp_f32_e32 v76, v76
	v_exp_f32_e32 v77, v77
	v_exp_f32_e32 v78, v78
	v_exp_f32_e32 v79, v79
	v_add_f32_e32 v76, 1.0, v76
	v_add_f32_e32 v77, 1.0, v77
	v_add_f32_e32 v82, 1.0, v78
	v_add_f32_e32 v79, 1.0, v79
	v_rcp_f32_e32 v78, v76
	v_rcp_f32_e32 v82, v82
	v_rcp_f32_e32 v83, v79
	v_rcp_f32_e32 v79, v77
	v_lshl_add_u64 v[76:77], s[4:5], 0, v[90:91]
	v_lshl_add_u64 v[76:77], v[76:77], 0, v[138:139]
	v_pk_mul_f32 v[84:85], v[88:89], v[82:83]
	v_pk_mul_f32 v[82:83], v[86:87], v[78:79]
	global_store_dwordx4 v[76:77], v[82:85], off
	s_nop 1
	v_mov_b64_e32 v[82:83], v[194:195]
	v_mov_b64_e32 v[84:85], v[196:197]
	s_nop 0
	s_nop 1
	v_mov_b64_e32 v[86:87], v[226:227]
	v_mov_b64_e32 v[88:89], v[228:229]
	v_add_f32_e32 v72, v72, v82
	v_add_f32_e32 v73, v73, v83
	v_add_f32_e32 v74, v74, v84
	v_add_f32_e32 v75, v75, v85
	v_mul_f32_e32 v72, 0xbfb8aa3b, v72
	v_mul_f32_e32 v73, 0xbfb8aa3b, v73
	v_mul_f32_e32 v74, 0xbfb8aa3b, v74
	v_mul_f32_e32 v75, 0xbfb8aa3b, v75
	v_exp_f32_e32 v72, v72
	v_exp_f32_e32 v73, v73
	v_exp_f32_e32 v74, v74
	v_exp_f32_e32 v75, v75
	v_add_f32_e32 v72, 1.0, v72
	v_add_f32_e32 v73, 1.0, v73
	v_add_f32_e32 v74, 1.0, v74
	v_add_f32_e32 v75, 1.0, v75
	v_rcp_f32_e32 v72, v72
;     __device__ __forceinline__ void operator()(const f32x4 (&acc)[2][2][4][2], const Unit& u, int wr, int wc, int fr, int fq) const {
;         const int col0 = u.pn * BM + wc * 32 + 4 * fq;
; #pragma unroll
;         for (int ai = 0; ai < 2; ++ai)
; #pragma unroll
;             for (int m = 0; m < 4; ++m) { const size_t row = (size_t)(u.pm * BM + ai * HALF + wr * 64 + m * 16 + fr);
; #pragma unroll
;                 for (int bj = 0; bj < 2; ++bj)
; #pragma unroll
;                     for (int n = 0; n < 2; ++n) { const int col = col0 + bj * HALF + n * 16; const f32x4 bv = *(const f32x4*)(bias + col), vv = *(const f32x4*)(V + row * ldv + col);
;                         const f32x4 z = acc[ai][bj][m][n] + bv; f32x4 o;
; #pragma unroll
;                         for (int j = 0; j < 4; ++j) o[j] = vv[j] * __builtin_amdgcn_rcpf(1.f + __expf(-z[j]));
;                         *(f32x4*)(Y + row * ldy + col) = o; } }
	v_rcp_f32_e32 v74, v74
	v_rcp_f32_e32 v75, v75
	v_rcp_f32_e32 v73, v73
	v_pk_mul_f32 v[74:75], v[88:89], v[74:75]
	v_pk_mul_f32 v[72:73], v[86:87], v[72:73]
	global_store_dwordx4 v[76:77], v[72:75], off offset:64
	s_nop 1
	v_mov_b64_e32 v[72:73], v[198:199]
	v_mov_b64_e32 v[74:75], v[200:201]
	s_nop 0
	s_nop 1
	v_mov_b64_e32 v[82:83], v[230:231]
	v_mov_b64_e32 v[84:85], v[232:233]
	v_add_f32_e32 v68, v68, v72
	v_add_f32_e32 v69, v69, v73
	v_add_f32_e32 v70, v70, v74
	v_add_f32_e32 v71, v71, v75
	v_mul_f32_e32 v68, 0xbfb8aa3b, v68
	v_mul_f32_e32 v69, 0xbfb8aa3b, v69
	v_mul_f32_e32 v70, 0xbfb8aa3b, v70
	v_mul_f32_e32 v71, 0xbfb8aa3b, v71
	v_exp_f32_e32 v68, v68
	v_exp_f32_e32 v69, v69
	v_exp_f32_e32 v70, v70
	v_exp_f32_e32 v71, v71
	v_add_f32_e32 v68, 1.0, v68
	v_add_f32_e32 v69, 1.0, v69
	v_add_f32_e32 v70, 1.0, v70
	v_add_f32_e32 v71, 1.0, v71
	v_rcp_f32_e32 v68, v68
	v_rcp_f32_e32 v70, v70
	v_rcp_f32_e32 v71, v71
	v_rcp_f32_e32 v69, v69
	v_pk_mul_f32 v[70:71], v[84:85], v[70:71]
	v_pk_mul_f32 v[68:69], v[82:83], v[68:69]
	global_store_dwordx4 v[76:77], v[68:71], off offset:512
	s_nop 1
	v_mov_b64_e32 v[68:69], v[202:203]
	v_mov_b64_e32 v[70:71], v[204:205]
	s_nop 0
	s_nop 1
	v_mov_b64_e32 v[72:73], v[234:235]
	v_mov_b64_e32 v[74:75], v[236:237]
	v_add_f32_e32 v64, v64, v68
	v_add_f32_e32 v65, v65, v69
	v_add_f32_e32 v66, v66, v70
	v_add_f32_e32 v67, v67, v71
	v_mul_f32_e32 v64, 0xbfb8aa3b, v64
	v_mul_f32_e32 v65, 0xbfb8aa3b, v65
	v_mul_f32_e32 v66, 0xbfb8aa3b, v66
	v_mul_f32_e32 v67, 0xbfb8aa3b, v67
	v_exp_f32_e32 v64, v64
	v_exp_f32_e32 v65, v65
	v_exp_f32_e32 v66, v66
	v_exp_f32_e32 v67, v67
	v_add_f32_e32 v64, 1.0, v64
	v_add_f32_e32 v65, 1.0, v65
	v_add_f32_e32 v66, 1.0, v66
	v_add_f32_e32 v67, 1.0, v67
	v_rcp_f32_e32 v64, v64
	v_rcp_f32_e32 v66, v66
	v_rcp_f32_e32 v67, v67
	v_rcp_f32_e32 v65, v65
	v_pk_mul_f32 v[66:67], v[74:75], v[66:67]
	v_pk_mul_f32 v[64:65], v[72:73], v[64:65]
	global_store_dwordx4 v[76:77], v[64:67], off offset:576
	s_nop 1
	v_mov_b64_e32 v[66:67], v[190:191]
	v_mov_b64_e32 v[68:69], v[192:193]
	v_add_u32_e32 v238, 0x80, v140
	v_mov_b32_e32 v239, 0
	v_lshlrev_b64 v[238:239], 11, v[238:239]
	v_lshl_add_u64 v[238:239], s[8:9], 0, v[238:239]
	v_lshl_add_u64 v[238:239], v[238:239], 0, v[138:139]
	global_load_dwordx4 v[206:209], v[238:239], off
	global_load_dwordx4 v[210:213], v[238:239], off offset:64
	global_load_dwordx4 v[214:217], v[238:239], off offset:512
	global_load_dwordx4 v[218:221], v[238:239], off offset:576
	v_add_u32_e32 v240, 0x90, v140
	v_mov_b32_e32 v241, 0
	v_lshlrev_b64 v[240:241], 11, v[240:241]
	v_lshl_add_u64 v[240:241], s[8:9], 0, v[240:241]
	v_lshl_add_u64 v[240:241], v[240:241], 0, v[138:139]
	global_load_dwordx4 v[222:225], v[240:241], off
	global_load_dwordx4 v[226:229], v[240:241], off offset:64
	global_load_dwordx4 v[230:233], v[240:241], off offset:512
	global_load_dwordx4 v[234:237], v[240:241], off offset:576
	s_waitcnt vmcnt(0)
	v_add_u32_e32 v74, 0x80, v140
	v_ashrrev_i32_e32 v75, 31, v74
	v_lshlrev_b64 v[64:65], 11, v[74:75]
	v_lshl_add_u64 v[64:65], s[8:9], 0, v[64:65]
	v_lshl_add_u64 v[64:65], v[64:65], 0, v[138:139]
	s_nop 1
	v_mov_b64_e32 v[70:71], v[206:207]
	v_mov_b64_e32 v[72:73], v[208:209]
	v_lshlrev_b64 v[74:75], 13, v[74:75]
	v_add_f32_e32 v60, v60, v66
	v_add_f32_e32 v61, v61, v67
	v_add_f32_e32 v62, v62, v68
	v_add_f32_e32 v63, v63, v69
	v_mul_f32_e32 v60, 0xbfb8aa3b, v60
	v_mul_f32_e32 v61, 0xbfb8aa3b, v61
	v_mul_f32_e32 v62, 0xbfb8aa3b, v62
	v_mul_f32_e32 v63, 0xbfb8aa3b, v63
	v_exp_f32_e32 v60, v60
	v_exp_f32_e32 v61, v61
	v_exp_f32_e32 v62, v62
	v_exp_f32_e32 v63, v63
	v_add_f32_e32 v60, 1.0, v60
	v_add_f32_e32 v61, 1.0, v61
	v_add_f32_e32 v66, 1.0, v62
	v_add_f32_e32 v63, 1.0, v63
	v_rcp_f32_e32 v62, v60
	v_rcp_f32_e32 v66, v66
	v_rcp_f32_e32 v67, v63
	v_rcp_f32_e32 v63, v61
	v_lshl_add_u64 v[60:61], s[4:5], 0, v[74:75]
	v_lshl_add_u64 v[60:61], v[60:61], 0, v[138:139]
	v_pk_mul_f32 v[68:69], v[72:73], v[66:67]
	v_pk_mul_f32 v[66:67], v[70:71], v[62:63]
	global_store_dwordx4 v[60:61], v[66:69], off
	s_nop 1
	v_mov_b64_e32 v[66:67], v[194:195]
	v_mov_b64_e32 v[68:69], v[196:197]
	s_nop 0
	s_nop 1
	v_mov_b64_e32 v[70:71], v[210:211]
	v_mov_b64_e32 v[72:73], v[212:213]
	v_add_f32_e32 v56, v56, v66
	v_add_f32_e32 v57, v57, v67
	v_add_f32_e32 v58, v58, v68
	v_add_f32_e32 v59, v59, v69
	v_mul_f32_e32 v56, 0xbfb8aa3b, v56
	v_mul_f32_e32 v57, 0xbfb8aa3b, v57
	v_mul_f32_e32 v58, 0xbfb8aa3b, v58
	v_mul_f32_e32 v59, 0xbfb8aa3b, v59
	v_exp_f32_e32 v56, v56
	v_exp_f32_e32 v57, v57
	v_exp_f32_e32 v58, v58
	v_exp_f32_e32 v59, v59
	v_add_f32_e32 v56, 1.0, v56
	v_add_f32_e32 v57, 1.0, v57
	v_add_f32_e32 v58, 1.0, v58
	v_add_f32_e32 v59, 1.0, v59
	v_rcp_f32_e32 v56, v56
	v_rcp_f32_e32 v58, v58
	v_rcp_f32_e32 v59, v59
	v_rcp_f32_e32 v57, v57
	v_pk_mul_f32 v[58:59], v[72:73], v[58:59]
	v_pk_mul_f32 v[56:57], v[70:71], v[56:57]
	global_store_dwordx4 v[60:61], v[56:59], off offset:64
	s_nop 1
	v_mov_b64_e32 v[56:57], v[198:199]
	v_mov_b64_e32 v[58:59], v[200:201]
	s_nop 0
	s_nop 1
	v_mov_b64_e32 v[66:67], v[214:215]
	v_mov_b64_e32 v[68:69], v[216:217]
	v_add_f32_e32 v52, v52, v56
	v_add_f32_e32 v53, v53, v57
	v_add_f32_e32 v54, v54, v58
	v_add_f32_e32 v55, v55, v59
	v_mul_f32_e32 v52, 0xbfb8aa3b, v52
	v_mul_f32_e32 v53, 0xbfb8aa3b, v53
	v_mul_f32_e32 v54, 0xbfb8aa3b, v54
	v_mul_f32_e32 v55, 0xbfb8aa3b, v55
	v_exp_f32_e32 v52, v52
	v_exp_f32_e32 v53, v53
	v_exp_f32_e32 v54, v54
	v_exp_f32_e32 v55, v55
	v_add_f32_e32 v52, 1.0, v52
	v_add_f32_e32 v53, 1.0, v53
	v_add_f32_e32 v54, 1.0, v54
	v_add_f32_e32 v55, 1.0, v55
	v_rcp_f32_e32 v52, v52
	v_rcp_f32_e32 v54, v54
	v_rcp_f32_e32 v55, v55
;     __device__ __forceinline__ void operator()(const f32x4 (&acc)[2][2][4][2], const Unit& u, int wr, int wc, int fr, int fq) const {
;         const int col0 = u.pn * BM + wc * 32 + 4 * fq;
; #pragma unroll
;         for (int ai = 0; ai < 2; ++ai)
; #pragma unroll
;             for (int m = 0; m < 4; ++m) { const size_t row = (size_t)(u.pm * BM + ai * HALF + wr * 64 + m * 16 + fr);
; #pragma unroll
;                 for (int bj = 0; bj < 2; ++bj)
; #pragma unroll
;                     for (int n = 0; n < 2; ++n) { const int col = col0 + bj * HALF + n * 16; const f32x4 bv = *(const f32x4*)(bias + col), vv = *(const f32x4*)(V + row * ldv + col);
;                         const f32x4 z = acc[ai][bj][m][n] + bv; f32x4 o;
; #pragma unroll
;                         for (int j = 0; j < 4; ++j) o[j] = vv[j] * __builtin_amdgcn_rcpf(1.f + __expf(-z[j]));
;                         *(f32x4*)(Y + row * ldy + col) = o; } }
	v_rcp_f32_e32 v53, v53
	v_pk_mul_f32 v[54:55], v[68:69], v[54:55]
	v_pk_mul_f32 v[52:53], v[66:67], v[52:53]
	global_store_dwordx4 v[60:61], v[52:55], off offset:512
	s_nop 1
	v_mov_b64_e32 v[52:53], v[202:203]
	v_mov_b64_e32 v[54:55], v[204:205]
	s_nop 0
	s_nop 1
	v_mov_b64_e32 v[56:57], v[218:219]
	v_mov_b64_e32 v[58:59], v[220:221]
	v_add_f32_e32 v48, v48, v52
	v_add_f32_e32 v49, v49, v53
	v_add_f32_e32 v50, v50, v54
	v_add_f32_e32 v51, v51, v55
	v_mul_f32_e32 v48, 0xbfb8aa3b, v48
	v_mul_f32_e32 v49, 0xbfb8aa3b, v49
	v_mul_f32_e32 v50, 0xbfb8aa3b, v50
	v_mul_f32_e32 v51, 0xbfb8aa3b, v51
	v_exp_f32_e32 v48, v48
	v_exp_f32_e32 v49, v49
	v_exp_f32_e32 v50, v50
	v_exp_f32_e32 v51, v51
	v_add_f32_e32 v48, 1.0, v48
	v_add_f32_e32 v49, 1.0, v49
	v_add_f32_e32 v50, 1.0, v50
	v_add_f32_e32 v51, 1.0, v51
	v_rcp_f32_e32 v48, v48
	v_rcp_f32_e32 v50, v50
	v_rcp_f32_e32 v51, v51
	v_rcp_f32_e32 v49, v49
	v_pk_mul_f32 v[50:51], v[58:59], v[50:51]
	v_pk_mul_f32 v[48:49], v[56:57], v[48:49]
	global_store_dwordx4 v[60:61], v[48:51], off offset:576
	s_nop 1
	v_mov_b64_e32 v[50:51], v[190:191]
	v_mov_b64_e32 v[52:53], v[192:193]
	v_add_u32_e32 v58, 0x90, v140
	v_ashrrev_i32_e32 v59, 31, v58
	v_lshlrev_b64 v[48:49], 11, v[58:59]
	v_lshl_add_u64 v[48:49], s[8:9], 0, v[48:49]
	v_lshl_add_u64 v[48:49], v[48:49], 0, v[138:139]
	s_nop 1
	v_mov_b64_e32 v[54:55], v[222:223]
	v_mov_b64_e32 v[56:57], v[224:225]
	v_lshlrev_b64 v[58:59], 13, v[58:59]
	v_add_f32_e32 v44, v44, v50
	v_add_f32_e32 v45, v45, v51
	v_add_f32_e32 v46, v46, v52
	v_add_f32_e32 v47, v47, v53
	v_mul_f32_e32 v44, 0xbfb8aa3b, v44
	v_mul_f32_e32 v45, 0xbfb8aa3b, v45
	v_mul_f32_e32 v46, 0xbfb8aa3b, v46
	v_mul_f32_e32 v47, 0xbfb8aa3b, v47
	v_exp_f32_e32 v44, v44
	v_exp_f32_e32 v45, v45
	v_exp_f32_e32 v46, v46
	v_exp_f32_e32 v47, v47
	v_add_f32_e32 v44, 1.0, v44
	v_add_f32_e32 v45, 1.0, v45
	v_add_f32_e32 v50, 1.0, v46
	v_add_f32_e32 v47, 1.0, v47
	v_rcp_f32_e32 v46, v44
	v_rcp_f32_e32 v50, v50
	v_rcp_f32_e32 v51, v47
	v_rcp_f32_e32 v47, v45
	v_lshl_add_u64 v[44:45], s[4:5], 0, v[58:59]
	v_lshl_add_u64 v[44:45], v[44:45], 0, v[138:139]
	v_pk_mul_f32 v[52:53], v[56:57], v[50:51]
	v_pk_mul_f32 v[50:51], v[54:55], v[46:47]
	global_store_dwordx4 v[44:45], v[50:53], off
	s_nop 1
	v_mov_b64_e32 v[50:51], v[194:195]
	v_mov_b64_e32 v[52:53], v[196:197]
	s_nop 0
	s_nop 1
	v_mov_b64_e32 v[54:55], v[226:227]
	v_mov_b64_e32 v[56:57], v[228:229]
	v_add_f32_e32 v40, v40, v50
	v_add_f32_e32 v41, v41, v51
	v_add_f32_e32 v42, v42, v52
	v_add_f32_e32 v43, v43, v53
	v_mul_f32_e32 v40, 0xbfb8aa3b, v40
	v_mul_f32_e32 v41, 0xbfb8aa3b, v41
	v_mul_f32_e32 v42, 0xbfb8aa3b, v42
	v_mul_f32_e32 v43, 0xbfb8aa3b, v43
	v_exp_f32_e32 v40, v40
	v_exp_f32_e32 v41, v41
	v_exp_f32_e32 v42, v42
	v_exp_f32_e32 v43, v43
	v_add_f32_e32 v40, 1.0, v40
	v_add_f32_e32 v41, 1.0, v41
	v_add_f32_e32 v42, 1.0, v42
	v_add_f32_e32 v43, 1.0, v43
	v_rcp_f32_e32 v40, v40
	v_rcp_f32_e32 v42, v42
	v_rcp_f32_e32 v43, v43
	v_rcp_f32_e32 v41, v41
	v_pk_mul_f32 v[42:43], v[56:57], v[42:43]
	v_pk_mul_f32 v[40:41], v[54:55], v[40:41]
	global_store_dwordx4 v[44:45], v[40:43], off offset:64
	s_nop 1
	v_mov_b64_e32 v[40:41], v[198:199]
	v_mov_b64_e32 v[42:43], v[200:201]
	s_nop 0
	s_nop 1
	v_mov_b64_e32 v[50:51], v[230:231]
	v_mov_b64_e32 v[52:53], v[232:233]
	v_add_f32_e32 v36, v36, v40
	v_add_f32_e32 v37, v37, v41
	v_add_f32_e32 v38, v38, v42
	v_add_f32_e32 v39, v39, v43
	v_mul_f32_e32 v36, 0xbfb8aa3b, v36
	v_mul_f32_e32 v37, 0xbfb8aa3b, v37
	v_mul_f32_e32 v38, 0xbfb8aa3b, v38
	v_mul_f32_e32 v39, 0xbfb8aa3b, v39
	v_exp_f32_e32 v36, v36
	v_exp_f32_e32 v37, v37
	v_exp_f32_e32 v38, v38
	v_exp_f32_e32 v39, v39
	v_add_f32_e32 v36, 1.0, v36
	v_add_f32_e32 v37, 1.0, v37
	v_add_f32_e32 v38, 1.0, v38
	v_add_f32_e32 v39, 1.0, v39
	v_rcp_f32_e32 v36, v36
	v_rcp_f32_e32 v38, v38
	v_rcp_f32_e32 v39, v39
	v_rcp_f32_e32 v37, v37
	v_pk_mul_f32 v[38:39], v[52:53], v[38:39]
	v_pk_mul_f32 v[36:37], v[50:51], v[36:37]
	global_store_dwordx4 v[44:45], v[36:39], off offset:512
	s_nop 1
	v_mov_b64_e32 v[36:37], v[202:203]
	v_mov_b64_e32 v[38:39], v[204:205]
	s_nop 0
	s_nop 1
	v_mov_b64_e32 v[40:41], v[234:235]
	v_mov_b64_e32 v[42:43], v[236:237]
	v_add_f32_e32 v32, v32, v36
	v_add_f32_e32 v33, v33, v37
	v_add_f32_e32 v34, v34, v38
	v_add_f32_e32 v35, v35, v39
	v_mul_f32_e32 v32, 0xbfb8aa3b, v32
	v_mul_f32_e32 v33, 0xbfb8aa3b, v33
	v_mul_f32_e32 v34, 0xbfb8aa3b, v34
	v_mul_f32_e32 v35, 0xbfb8aa3b, v35
	v_exp_f32_e32 v32, v32
	v_exp_f32_e32 v33, v33
	v_exp_f32_e32 v34, v34
	v_exp_f32_e32 v35, v35
	v_add_f32_e32 v32, 1.0, v32
	v_add_f32_e32 v33, 1.0, v33
	v_add_f32_e32 v34, 1.0, v34
	v_add_f32_e32 v35, 1.0, v35
	v_rcp_f32_e32 v32, v32
	v_rcp_f32_e32 v34, v34
	v_rcp_f32_e32 v35, v35
	v_rcp_f32_e32 v33, v33
	v_pk_mul_f32 v[34:35], v[42:43], v[34:35]
	v_pk_mul_f32 v[32:33], v[40:41], v[32:33]
	global_store_dwordx4 v[44:45], v[32:35], off offset:576
	s_nop 1
	v_mov_b64_e32 v[34:35], v[190:191]
	v_mov_b64_e32 v[36:37], v[192:193]
	v_add_u32_e32 v238, 0xa0, v140
	v_mov_b32_e32 v239, 0
	v_lshlrev_b64 v[238:239], 11, v[238:239]
	v_lshl_add_u64 v[238:239], s[8:9], 0, v[238:239]
	v_lshl_add_u64 v[238:239], v[238:239], 0, v[138:139]
	global_load_dwordx4 v[206:209], v[238:239], off
	global_load_dwordx4 v[210:213], v[238:239], off offset:64
	global_load_dwordx4 v[214:217], v[238:239], off offset:512
	global_load_dwordx4 v[218:221], v[238:239], off offset:576
	v_add_u32_e32 v240, 0xb0, v140
	v_mov_b32_e32 v241, 0
	v_lshlrev_b64 v[240:241], 11, v[240:241]
	v_lshl_add_u64 v[240:241], s[8:9], 0, v[240:241]
	v_lshl_add_u64 v[240:241], v[240:241], 0, v[138:139]
	global_load_dwordx4 v[222:225], v[240:241], off
	global_load_dwordx4 v[226:229], v[240:241], off offset:64
	global_load_dwordx4 v[230:233], v[240:241], off offset:512
	global_load_dwordx4 v[234:237], v[240:241], off offset:576
	s_waitcnt vmcnt(0)
;     __device__ __forceinline__ void operator()(const f32x4 (&acc)[2][2][4][2], const Unit& u, int wr, int wc, int fr, int fq) const {
;         const int col0 = u.pn * BM + wc * 32 + 4 * fq;
; #pragma unroll
;         for (int ai = 0; ai < 2; ++ai)
; #pragma unroll
;             for (int m = 0; m < 4; ++m) { const size_t row = (size_t)(u.pm * BM + ai * HALF + wr * 64 + m * 16 + fr);
; #pragma unroll
;                 for (int bj = 0; bj < 2; ++bj)
; #pragma unroll
;                     for (int n = 0; n < 2; ++n) { const int col = col0 + bj * HALF + n * 16; const f32x4 bv = *(const f32x4*)(bias + col), vv = *(const f32x4*)(V + row * ldv + col);
;                         const f32x4 z = acc[ai][bj][m][n] + bv; f32x4 o;
; #pragma unroll
;                         for (int j = 0; j < 4; ++j) o[j] = vv[j] * __builtin_amdgcn_rcpf(1.f + __expf(-z[j]));
;                         *(f32x4*)(Y + row * ldy + col) = o; } }
	v_add_u32_e32 v42, 0xa0, v140
	v_ashrrev_i32_e32 v43, 31, v42
	v_lshlrev_b64 v[32:33], 11, v[42:43]
	v_lshl_add_u64 v[32:33], s[8:9], 0, v[32:33]
	v_lshl_add_u64 v[32:33], v[32:33], 0, v[138:139]
	s_nop 1
	v_mov_b64_e32 v[38:39], v[206:207]
	v_mov_b64_e32 v[40:41], v[208:209]
	v_lshlrev_b64 v[42:43], 13, v[42:43]
	v_add_f32_e32 v28, v28, v34
	v_add_f32_e32 v29, v29, v35
	v_add_f32_e32 v30, v30, v36
	v_add_f32_e32 v31, v31, v37
	v_mul_f32_e32 v28, 0xbfb8aa3b, v28
	v_mul_f32_e32 v29, 0xbfb8aa3b, v29
	v_mul_f32_e32 v30, 0xbfb8aa3b, v30
	v_mul_f32_e32 v31, 0xbfb8aa3b, v31
	v_exp_f32_e32 v28, v28
	v_exp_f32_e32 v29, v29
	v_exp_f32_e32 v30, v30
	v_exp_f32_e32 v31, v31
	v_add_f32_e32 v28, 1.0, v28
	v_add_f32_e32 v29, 1.0, v29
	v_add_f32_e32 v34, 1.0, v30
	v_add_f32_e32 v31, 1.0, v31
	v_rcp_f32_e32 v30, v28
	v_rcp_f32_e32 v34, v34
	v_rcp_f32_e32 v35, v31
	v_rcp_f32_e32 v31, v29
	v_lshl_add_u64 v[28:29], s[4:5], 0, v[42:43]
	v_lshl_add_u64 v[28:29], v[28:29], 0, v[138:139]
	v_pk_mul_f32 v[36:37], v[40:41], v[34:35]
	v_pk_mul_f32 v[34:35], v[38:39], v[30:31]
	global_store_dwordx4 v[28:29], v[34:37], off
	s_nop 1
	v_mov_b64_e32 v[34:35], v[194:195]
	v_mov_b64_e32 v[36:37], v[196:197]
	s_nop 0
	s_nop 1
	v_mov_b64_e32 v[38:39], v[210:211]
	v_mov_b64_e32 v[40:41], v[212:213]
	v_add_f32_e32 v24, v24, v34
	v_add_f32_e32 v25, v25, v35
	v_add_f32_e32 v26, v26, v36
	v_add_f32_e32 v27, v27, v37
	v_mul_f32_e32 v24, 0xbfb8aa3b, v24
	v_mul_f32_e32 v25, 0xbfb8aa3b, v25
	v_mul_f32_e32 v26, 0xbfb8aa3b, v26
	v_mul_f32_e32 v27, 0xbfb8aa3b, v27
	v_exp_f32_e32 v24, v24
	v_exp_f32_e32 v25, v25
	v_exp_f32_e32 v26, v26
	v_exp_f32_e32 v27, v27
	v_add_f32_e32 v24, 1.0, v24
	v_add_f32_e32 v25, 1.0, v25
	v_add_f32_e32 v26, 1.0, v26
	v_add_f32_e32 v27, 1.0, v27
	v_rcp_f32_e32 v24, v24
	v_rcp_f32_e32 v26, v26
	v_rcp_f32_e32 v27, v27
	v_rcp_f32_e32 v25, v25
	v_pk_mul_f32 v[26:27], v[40:41], v[26:27]
	v_pk_mul_f32 v[24:25], v[38:39], v[24:25]
	global_store_dwordx4 v[28:29], v[24:27], off offset:64
	s_nop 1
	v_mov_b64_e32 v[24:25], v[198:199]
	v_mov_b64_e32 v[26:27], v[200:201]
	s_nop 0
	s_nop 1
	v_mov_b64_e32 v[34:35], v[214:215]
	v_mov_b64_e32 v[36:37], v[216:217]
	v_add_f32_e32 v20, v20, v24
	v_add_f32_e32 v21, v21, v25
	v_add_f32_e32 v22, v22, v26
	v_add_f32_e32 v23, v23, v27
	v_mul_f32_e32 v20, 0xbfb8aa3b, v20
	v_mul_f32_e32 v21, 0xbfb8aa3b, v21
	v_mul_f32_e32 v22, 0xbfb8aa3b, v22
	v_mul_f32_e32 v23, 0xbfb8aa3b, v23
	v_exp_f32_e32 v20, v20
	v_exp_f32_e32 v21, v21
	v_exp_f32_e32 v22, v22
	v_exp_f32_e32 v23, v23
	v_add_f32_e32 v20, 1.0, v20
	v_add_f32_e32 v21, 1.0, v21
	v_add_f32_e32 v22, 1.0, v22
	v_add_f32_e32 v23, 1.0, v23
	v_rcp_f32_e32 v20, v20
	v_rcp_f32_e32 v22, v22
	v_rcp_f32_e32 v23, v23
	v_rcp_f32_e32 v21, v21
	v_pk_mul_f32 v[22:23], v[36:37], v[22:23]
	v_pk_mul_f32 v[20:21], v[34:35], v[20:21]
	global_store_dwordx4 v[28:29], v[20:23], off offset:512
	s_nop 1
	v_mov_b64_e32 v[20:21], v[202:203]
	v_mov_b64_e32 v[22:23], v[204:205]
	s_nop 0
	s_nop 1
	v_mov_b64_e32 v[24:25], v[218:219]
	v_mov_b64_e32 v[26:27], v[220:221]
	v_add_f32_e32 v16, v16, v20
	v_add_f32_e32 v17, v17, v21
	v_add_f32_e32 v18, v18, v22
	v_add_f32_e32 v19, v19, v23
	v_mul_f32_e32 v16, 0xbfb8aa3b, v16
	v_mul_f32_e32 v17, 0xbfb8aa3b, v17
	v_mul_f32_e32 v18, 0xbfb8aa3b, v18
	v_mul_f32_e32 v19, 0xbfb8aa3b, v19
	v_exp_f32_e32 v16, v16
	v_exp_f32_e32 v17, v17
	v_exp_f32_e32 v18, v18
	v_exp_f32_e32 v19, v19
	v_add_f32_e32 v16, 1.0, v16
	v_add_f32_e32 v17, 1.0, v17
	v_add_f32_e32 v18, 1.0, v18
	v_add_f32_e32 v19, 1.0, v19
	v_rcp_f32_e32 v16, v16
	v_rcp_f32_e32 v18, v18
	v_rcp_f32_e32 v19, v19
	v_rcp_f32_e32 v17, v17
	v_pk_mul_f32 v[18:19], v[26:27], v[18:19]
	v_pk_mul_f32 v[16:17], v[24:25], v[16:17]
	global_store_dwordx4 v[28:29], v[16:19], off offset:576
	s_nop 1
	v_mov_b64_e32 v[18:19], v[190:191]
; #define PG8_BAR __builtin_amdgcn_s_barrier()
; template <class Epi, class Sched, bool ALIGN_EPI = false, bool SP2 = false>
; __device__ __forceinline__ void gemm_phase(PG8_LAS unsigned char* lds, const Gemm g, const Sched& S, const Epi& E) {
;     ...
;         if constexpr (ALIGN_EPI) { if (wr == 0) PG8_BAR; }
;         if constexpr (!Epi::AFTER_DRAIN) { E(acc, cur, wr, wc, fr, fq); S.done(cur); }
;         if (!has_next) break;
; #pragma unroll
;         for (int a = 0; a < 2; ++a)
; #pragma unroll
;             for (int b = 0; b < 2; ++b)
; #pragma unroll
;                 for (int m = 0; m < 4; ++m)
; #pragma unroll
;                     for (int n = 0; n < 2; ++n) acc[a][b][m][n] = (f32x4){0.f, 0.f, 0.f, 0.f};
;         cur = nxt; cA = nA; cB = nB; ++ui;
;         if constexpr (ALIGN_EPI) { if (wr == 1) PG8_BAR; }
;     __device__ __forceinline__ void operator()(const f32x4 (&acc)[2][2][4][2], const Unit& u, int wr, int wc, int fr, int fq) const {
;         const int col0 = u.pn * BM + wc * 32 + 4 * fq;
; #pragma unroll
;         for (int ai = 0; ai < 2; ++ai)
; #pragma unroll
;             for (int m = 0; m < 4; ++m) { const size_t row = (size_t)(u.pm * BM + ai * HALF + wr * 64 + m * 16 + fr);
; #pragma unroll
;                 for (int bj = 0; bj < 2; ++bj)
; #pragma unroll
;                     for (int n = 0; n < 2; ++n) { const int col = col0 + bj * HALF + n * 16; const f32x4 bv = *(const f32x4*)(bias + col), vv = *(const f32x4*)(V + row * ldv + col);
;                         const f32x4 z = acc[ai][bj][m][n] + bv; f32x4 o;
; #pragma unroll
;                         for (int j = 0; j < 4; ++j) o[j] = vv[j] * __builtin_amdgcn_rcpf(1.f + __expf(-z[j]));
;                         *(f32x4*)(Y + row * ldy + col) = o; } }
	v_mov_b64_e32 v[20:21], v[192:193]
	v_add_u32_e32 v26, 0xb0, v140
	v_ashrrev_i32_e32 v27, 31, v26
	v_lshlrev_b64 v[16:17], 11, v[26:27]
	v_lshl_add_u64 v[16:17], s[8:9], 0, v[16:17]
	v_lshl_add_u64 v[16:17], v[16:17], 0, v[138:139]
	s_nop 1
	v_mov_b64_e32 v[22:23], v[222:223]
	v_mov_b64_e32 v[24:25], v[224:225]
	v_lshlrev_b64 v[26:27], 13, v[26:27]
	v_add_f32_e32 v12, v12, v18
	v_add_f32_e32 v13, v13, v19
	v_add_f32_e32 v14, v14, v20
	v_add_f32_e32 v15, v15, v21
	v_mul_f32_e32 v12, 0xbfb8aa3b, v12
	v_mul_f32_e32 v13, 0xbfb8aa3b, v13
	v_mul_f32_e32 v14, 0xbfb8aa3b, v14
	v_mul_f32_e32 v15, 0xbfb8aa3b, v15
	v_exp_f32_e32 v12, v12
	v_exp_f32_e32 v13, v13
	v_exp_f32_e32 v14, v14
	v_exp_f32_e32 v15, v15
	v_add_f32_e32 v12, 1.0, v12
	v_add_f32_e32 v13, 1.0, v13
	v_add_f32_e32 v18, 1.0, v14
	v_add_f32_e32 v15, 1.0, v15
	v_rcp_f32_e32 v14, v12
	v_rcp_f32_e32 v18, v18
	v_rcp_f32_e32 v19, v15
	v_rcp_f32_e32 v15, v13
	v_lshl_add_u64 v[12:13], s[4:5], 0, v[26:27]
	v_lshl_add_u64 v[12:13], v[12:13], 0, v[138:139]
	v_pk_mul_f32 v[20:21], v[24:25], v[18:19]
	v_pk_mul_f32 v[18:19], v[22:23], v[14:15]
	global_store_dwordx4 v[12:13], v[18:21], off
	s_nop 1
	v_mov_b64_e32 v[18:19], v[194:195]
	v_mov_b64_e32 v[20:21], v[196:197]
	s_nop 0
	s_nop 1
	v_mov_b64_e32 v[22:23], v[226:227]
	v_mov_b64_e32 v[24:25], v[228:229]
	v_add_f32_e32 v8, v8, v18
	v_add_f32_e32 v9, v9, v19
	v_add_f32_e32 v10, v10, v20
	v_add_f32_e32 v11, v11, v21
	v_mul_f32_e32 v8, 0xbfb8aa3b, v8
	v_mul_f32_e32 v9, 0xbfb8aa3b, v9
	v_mul_f32_e32 v10, 0xbfb8aa3b, v10
	v_mul_f32_e32 v11, 0xbfb8aa3b, v11
	v_exp_f32_e32 v8, v8
	v_exp_f32_e32 v9, v9
	v_exp_f32_e32 v10, v10
	v_exp_f32_e32 v11, v11
	v_add_f32_e32 v8, 1.0, v8
	v_add_f32_e32 v9, 1.0, v9
	v_add_f32_e32 v10, 1.0, v10
	v_add_f32_e32 v11, 1.0, v11
	v_rcp_f32_e32 v8, v8
	v_rcp_f32_e32 v10, v10
	v_rcp_f32_e32 v11, v11
	v_rcp_f32_e32 v9, v9
	v_pk_mul_f32 v[10:11], v[24:25], v[10:11]
	v_pk_mul_f32 v[8:9], v[22:23], v[8:9]
	global_store_dwordx4 v[12:13], v[8:11], off offset:64
	s_nop 1
	v_mov_b64_e32 v[8:9], v[198:199]
	v_mov_b64_e32 v[10:11], v[200:201]
	s_nop 0
	s_nop 1
	v_mov_b64_e32 v[18:19], v[230:231]
	v_mov_b64_e32 v[20:21], v[232:233]
	v_add_f32_e32 v4, v4, v8
	v_add_f32_e32 v5, v5, v9
	v_add_f32_e32 v6, v6, v10
	v_add_f32_e32 v7, v7, v11
	v_mul_f32_e32 v4, 0xbfb8aa3b, v4
	v_mul_f32_e32 v5, 0xbfb8aa3b, v5
	v_mul_f32_e32 v6, 0xbfb8aa3b, v6
	v_mul_f32_e32 v7, 0xbfb8aa3b, v7
	v_exp_f32_e32 v4, v4
	v_exp_f32_e32 v5, v5
	v_exp_f32_e32 v6, v6
	v_exp_f32_e32 v7, v7
	v_add_f32_e32 v4, 1.0, v4
	v_add_f32_e32 v5, 1.0, v5
	v_add_f32_e32 v6, 1.0, v6
	v_add_f32_e32 v7, 1.0, v7
	v_rcp_f32_e32 v4, v4
	v_rcp_f32_e32 v6, v6
	v_rcp_f32_e32 v7, v7
	v_rcp_f32_e32 v5, v5
	v_pk_mul_f32 v[6:7], v[20:21], v[6:7]
	v_pk_mul_f32 v[4:5], v[18:19], v[4:5]
	global_store_dwordx4 v[12:13], v[4:7], off offset:512
	s_nop 1
	v_mov_b64_e32 v[4:5], v[202:203]
	v_mov_b64_e32 v[6:7], v[204:205]
	s_nop 0
	s_nop 1
	v_mov_b64_e32 v[8:9], v[234:235]
	v_mov_b64_e32 v[10:11], v[236:237]
	v_add_f32_e32 v0, v0, v4
	v_add_f32_e32 v1, v1, v5
	v_add_f32_e32 v2, v2, v6
	v_add_f32_e32 v3, v3, v7
	v_mul_f32_e32 v0, 0xbfb8aa3b, v0
	v_mul_f32_e32 v1, 0xbfb8aa3b, v1
	v_mul_f32_e32 v2, 0xbfb8aa3b, v2
	v_mul_f32_e32 v3, 0xbfb8aa3b, v3
	v_exp_f32_e32 v0, v0
	v_exp_f32_e32 v1, v1
	v_exp_f32_e32 v2, v2
	v_exp_f32_e32 v3, v3
	v_add_f32_e32 v0, 1.0, v0
	v_add_f32_e32 v1, 1.0, v1
	v_add_f32_e32 v2, 1.0, v2
	v_add_f32_e32 v3, 1.0, v3
	v_rcp_f32_e32 v0, v0
	v_rcp_f32_e32 v2, v2
	v_rcp_f32_e32 v3, v3
	v_rcp_f32_e32 v1, v1
	v_pk_mul_f32 v[2:3], v[10:11], v[2:3]
	v_pk_mul_f32 v[0:1], v[8:9], v[0:1]
	global_store_dwordx4 v[12:13], v[0:3], off offset:576
	s_cbranch_vccnz .LBB0_125
	s_andn2_b64 vcc, exec, s[6:7]
	s_cbranch_vccnz .LBB0_124
	s_barrier
	s_branch .LBB0_124

; __device__ __forceinline__ unsigned cvt_pk_bf16(float lo, float hi) { unsigned r; asm volatile("v_cvt_pk_bf16_f32 %0, %1, %2" : "=v"(r) : "v"(lo), "v"(hi)); return r; }
; __device__ __forceinline__ float dot4(f32x4 a, f32x4 b) { return (a.x * b.x + a.y * b.y) + (a.z * b.z + a.w * b.w); }
; __device__ __forceinline__ void prep_rows(const float* src, const float* g, bf16* dst, float* copy_dst, float* SS, int gw, int NGW, int lane) {
;     for (int m = gw; m < T; m += NGW) {
;         const f32x4* xr = (const f32x4*)(src + (size_t)m * D) + lane;
;         f32x4 v[8]; float s = 0.f;
; #pragma unroll
;         for (int j = 0; j < 8; ++j) { v[j] = xr[64 * j]; s += dot4(v[j], v[j]); }
;         s = wave_sum(s);
;         if (lane == 0) SS[m] = s;
; #pragma unroll
;         for (int j = 0; j < 8; ++j) { const f32x4 gg = ((const f32x4*)g)[lane + 64 * j]; const f32x4 o = v[j] * gg;
;             u32x2 w; w.x = pg8::cvt_pk_bf16(o.x, o.y); w.y = pg8::cvt_pk_bf16(o.z, o.w);
;             ((u32x2*)(dst + (size_t)m * D))[lane + 64 * j] = w; }
;     }
.LBB0_615:
	s_or_b64 exec, exec, s[8:9]
	s_waitcnt lgkmcnt(0)
	global_load_dwordx4 v[54:57], v[34:35], off
	global_load_dwordx4 v[96:99], v[34:35], off offset:1024
	global_load_dwordx4 v[100:103], v[34:35], off offset:2048
	global_load_dwordx4 v[104:107], v[34:35], off offset:3072
	global_load_dwordx4 v[108:111], v[36:37], off
	global_load_dwordx4 v[112:115], v[38:39], off
	global_load_dwordx4 v[116:119], v[40:41], off
	global_load_dwordx4 v[120:123], v[42:43], off
	v_lshl_add_u64 v[58:59], s[18:19], 0, v[44:45]
	s_mov_b32 s8, 0xa200000
	v_add_co_u32_e32 v58, vcc, s8, v58
	s_add_i32 s16, s16, s12
	s_nop 0
	v_addc_co_u32_e32 v59, vcc, 0, v59, vcc
	s_add_u32 s10, s10, s0
	s_addc_u32 s11, s11, s1
	s_mov_b32 s14, s12
	v_lshl_add_u64 v[44:45], v[44:45], 0, s[4:5]
	s_cmpk_lt_i32 s16, 0x2000
	v_lshl_add_u64 v[46:47], v[46:47], 0, s[6:7]
	s_waitcnt vmcnt(7)
	v_pk_mul_f32 v[28:29], v[28:29], v[54:55]
	v_pk_mul_f32 v[30:31], v[30:31], v[56:57]
	v_cvt_pk_bf16_f32 v28, v28, v29
	s_nop 0
	v_cvt_pk_bf16_f32 v29, v30, v31
	global_store_dwordx2 v[58:59], v[28:29], off
	s_waitcnt vmcnt(7)
	s_nop 1
	v_mov_b64_e32 v[28:29], v[96:97]
	v_mov_b64_e32 v[30:31], v[98:99]
	v_pk_mul_f32 v[24:25], v[24:25], v[28:29]
	v_pk_mul_f32 v[26:27], v[26:27], v[30:31]
	v_cvt_pk_bf16_f32 v24, v24, v25
	s_nop 0
	v_cvt_pk_bf16_f32 v25, v26, v27
	global_store_dwordx2 v[58:59], v[24:25], off offset:512
	s_waitcnt vmcnt(7)
	s_nop 1
	v_mov_b64_e32 v[24:25], v[100:101]
	v_mov_b64_e32 v[26:27], v[102:103]
	v_pk_mul_f32 v[20:21], v[20:21], v[24:25]
	v_pk_mul_f32 v[22:23], v[22:23], v[26:27]
	v_cvt_pk_bf16_f32 v20, v20, v21
	s_nop 0
	v_cvt_pk_bf16_f32 v21, v22, v23
	global_store_dwordx2 v[58:59], v[20:21], off offset:1024
	s_waitcnt vmcnt(7)
	s_nop 1
	v_mov_b64_e32 v[20:21], v[104:105]
	v_mov_b64_e32 v[22:23], v[106:107]
	v_pk_mul_f32 v[16:17], v[16:17], v[20:21]
	v_pk_mul_f32 v[18:19], v[18:19], v[22:23]
	v_cvt_pk_bf16_f32 v16, v16, v17
	s_nop 0
	v_cvt_pk_bf16_f32 v17, v18, v19
	global_store_dwordx2 v[58:59], v[16:17], off offset:1536
	s_waitcnt vmcnt(7)
	s_nop 1
	v_mov_b64_e32 v[16:17], v[108:109]
	v_mov_b64_e32 v[18:19], v[110:111]
	v_pk_mul_f32 v[12:13], v[12:13], v[16:17]
	v_pk_mul_f32 v[14:15], v[14:15], v[18:19]
	v_cvt_pk_bf16_f32 v12, v12, v13
	s_nop 0
	v_cvt_pk_bf16_f32 v13, v14, v15
	global_store_dwordx2 v[58:59], v[12:13], off offset:2048
	s_waitcnt vmcnt(7)
	s_nop 1
	v_mov_b64_e32 v[12:13], v[112:113]
	v_mov_b64_e32 v[14:15], v[114:115]
	v_pk_mul_f32 v[8:9], v[8:9], v[12:13]
	v_pk_mul_f32 v[10:11], v[10:11], v[14:15]
	v_cvt_pk_bf16_f32 v8, v8, v9
	s_nop 0
	v_cvt_pk_bf16_f32 v9, v10, v11
	global_store_dwordx2 v[58:59], v[8:9], off offset:2560
	s_waitcnt vmcnt(7)
	s_nop 1
	v_mov_b64_e32 v[8:9], v[116:117]
	v_mov_b64_e32 v[10:11], v[118:119]
	v_pk_mul_f32 v[4:5], v[4:5], v[8:9]
	v_pk_mul_f32 v[6:7], v[6:7], v[10:11]
	v_cvt_pk_bf16_f32 v4, v4, v5
	s_nop 0
	v_cvt_pk_bf16_f32 v5, v6, v7
	global_store_dwordx2 v[58:59], v[4:5], off offset:3072
	s_waitcnt vmcnt(7)
	s_nop 1
	v_mov_b64_e32 v[4:5], v[120:121]
	v_mov_b64_e32 v[6:7], v[122:123]
	v_pk_mul_f32 v[0:1], v[0:1], v[4:5]
	v_pk_mul_f32 v[2:3], v[2:3], v[6:7]
	v_cvt_pk_bf16_f32 v0, v0, v1
	s_nop 0
	v_cvt_pk_bf16_f32 v1, v2, v3
	global_store_dwordx2 v[58:59], v[0:1], off offset:3584
	s_cbranch_scc0 .LBB0_618
